# PEER query GEMM k-loop: LDS-write ladder no longer waits for the 8 loads issued at the top of the same trip (first half emitted per path with exact vmcnt counts; end-of-trip writes wait vmcnt(8))
# baseline (speedup 1.0000x reference)
.LBB0_1849:
	s_add_i32 s3, s3, 2
	s_cmp_lt_u32 s3, 14
	s_cselect_b64 s[8:9], -1, 0
	s_cmp_gt_u32 s3, 13
	s_cselect_b64 s[6:7], -1, 0
	s_and_b64 vcc, exec, s[6:7]
	v_lshl_add_u64 v[180:181], v[162:163], 0, v[32:33]
	v_lshl_add_u64 v[184:185], v[178:179], 0, v[32:33]
	v_lshl_add_u64 v[182:183], v[172:173], 0, v[32:33]
	s_cbranch_vccnz .LBB0_1851
	v_add_co_u32_e32 v74, vcc, 0x10000, v180
	v_lshl_add_u64 v[66:67], v[174:175], 0, v[32:33]
	s_nop 0
	v_addc_co_u32_e32 v75, vcc, 0, v181, vcc
	v_add_co_u32_e32 v78, vcc, 0x20000, v180
	v_lshl_add_u64 v[70:71], v[176:177], 0, v[32:33]
	s_nop 0
	v_addc_co_u32_e32 v79, vcc, 0, v181, vcc
	v_add_co_u32_e32 v90, vcc, 0x30000, v180
	global_load_dwordx4 v[66:69], v[66:67], off
	s_nop 0
	v_addc_co_u32_e32 v91, vcc, 0, v181, vcc
	global_load_dwordx4 v[70:73], v[70:71], off
	s_nop 0
	global_load_dwordx4 v[86:89], v[184:185], off
	s_nop 0
	global_load_dwordx4 v[74:77], v[74:75], off offset:256
	s_nop 0
	global_load_dwordx4 v[82:85], v[78:79], off offset:256
	global_load_dwordx4 v[94:97], v[182:183], off offset:-128
	s_nop 0
	global_load_dwordx4 v[78:81], v[180:181], off offset:256
	s_nop 0
	global_load_dwordx4 v[90:93], v[90:91], off offset:256
	s_setprio 2
	ds_read_b128 v[194:197], v164 offset:36864
	ds_read_b128 v[224:227], v189
	ds_read_b128 v[228:231], v189 offset:4608
	ds_read_b128 v[232:235], v189 offset:9216
	ds_read_b128 v[236:239], v189 offset:13824
	s_cmp_gt_u32 s3, 12
	ds_read_b128 v[240:243], v164 offset:36896
	ds_read_b128 v[190:193], v189 offset:32
	s_waitcnt lgkmcnt(5)
	v_mfma_f32_32x32x16_bf16 v[0:15], v[224:227], v[194:197], v[0:15]
	ds_read_b128 v[198:201], v189 offset:4640
	s_waitcnt lgkmcnt(5)
	v_mfma_f32_32x32x16_bf16 v[16:31], v[228:231], v[194:197], v[16:31]
	ds_read_b128 v[224:227], v189 offset:9248
	s_waitcnt lgkmcnt(5)
	v_mfma_f32_32x32x16_bf16 v[34:49], v[232:235], v[194:197], v[34:49]
	ds_read_b128 v[228:231], v189 offset:13856
	s_waitcnt lgkmcnt(5)
	v_mfma_f32_32x32x16_bf16 v[50:65], v[236:239], v[194:197], v[50:65]
	ds_read_b128 v[194:197], v164 offset:36928
	ds_read_b128 v[232:235], v189 offset:64
	s_waitcnt lgkmcnt(5)
	v_mfma_f32_32x32x16_bf16 v[0:15], v[190:193], v[240:243], v[0:15]
	ds_read_b128 v[236:239], v189 offset:4672
	s_waitcnt lgkmcnt(5)
	v_mfma_f32_32x32x16_bf16 v[16:31], v[198:201], v[240:243], v[16:31]
	ds_read_b128 v[190:193], v189 offset:9280
	s_waitcnt lgkmcnt(5)
	v_mfma_f32_32x32x16_bf16 v[34:49], v[224:227], v[240:243], v[34:49]
	ds_read_b128 v[198:201], v189 offset:13888
	s_waitcnt lgkmcnt(5)
	v_mfma_f32_32x32x16_bf16 v[50:65], v[228:231], v[240:243], v[50:65]
	ds_read_b128 v[240:243], v164 offset:36960
	ds_read_b128 v[224:227], v189 offset:96
	s_waitcnt lgkmcnt(5)
	v_mfma_f32_32x32x16_bf16 v[0:15], v[232:235], v[194:197], v[0:15]
	ds_read_b128 v[228:231], v189 offset:4704
	s_waitcnt lgkmcnt(5)
	v_mfma_f32_32x32x16_bf16 v[16:31], v[236:239], v[194:197], v[16:31]
	ds_read_b128 v[232:235], v189 offset:9312
	s_waitcnt lgkmcnt(5)
	v_mfma_f32_32x32x16_bf16 v[34:49], v[190:193], v[194:197], v[34:49]
	ds_read_b128 v[236:239], v189 offset:13920
	s_waitcnt lgkmcnt(5)
	v_mfma_f32_32x32x16_bf16 v[50:65], v[198:201], v[194:197], v[50:65]
	s_waitcnt lgkmcnt(3)
	v_mfma_f32_32x32x16_bf16 v[0:15], v[224:227], v[240:243], v[0:15]
	s_waitcnt lgkmcnt(2)
	v_mfma_f32_32x32x16_bf16 v[16:31], v[228:231], v[240:243], v[16:31]
	s_setprio 0
	s_waitcnt vmcnt(15)
	ds_write_b128 v166, v[130:133] offset:18432
	s_waitcnt vmcnt(9)
	ds_write_b128 v166, v[138:141] offset:55296
	s_waitcnt vmcnt(13)
	ds_write_b128 v166, v[134:137] offset:23040
	s_waitcnt vmcnt(12)
	ds_write_b128 v166, v[146:149] offset:59904
	s_waitcnt vmcnt(11)
	ds_write_b128 v166, v[142:145] offset:27648
	s_waitcnt vmcnt(10)
	ds_write_b128 v166, v[150:153] offset:64512
	s_waitcnt vmcnt(9)
	ds_write_b128 v166, v[154:157] offset:32256
	s_waitcnt vmcnt(8)
	ds_write_b128 v165, v[158:161] offset:13824
	s_waitcnt lgkmcnt(0)
	s_barrier
	v_mfma_f32_32x32x16_bf16 v[34:49], v[232:235], v[240:243], v[34:49]
	v_mfma_f32_32x32x16_bf16 v[50:65], v[236:239], v[240:243], v[50:65]
	s_branch .Lqs1851_join

.Lqs1851_join:
	s_cbranch_scc1 .LBB0_1853
	v_add_co_u32_e32 v138, vcc, 0x10000, v180
	v_lshl_add_u64 v[130:131], v[168:169], 0, v[32:33]
	s_nop 0
	v_addc_co_u32_e32 v139, vcc, 0, v181, vcc
	v_add_co_u32_e32 v140, vcc, 0x20000, v180
	v_lshl_add_u64 v[134:135], v[170:171], 0, v[32:33]
	s_nop 0
	v_addc_co_u32_e32 v141, vcc, 0, v181, vcc
	v_add_co_u32_e32 v158, vcc, 0x30000, v180
	global_load_dwordx4 v[130:133], v[130:131], off
	s_nop 0
	v_addc_co_u32_e32 v159, vcc, 0, v181, vcc
	global_load_dwordx4 v[134:137], v[134:135], off
	s_nop 0
	global_load_dwordx4 v[142:145], v[184:185], off offset:128
	global_load_dwordx4 v[146:149], v[138:139], off offset:384
	global_load_dwordx4 v[150:153], v[140:141], off offset:384
	global_load_dwordx4 v[154:157], v[182:183], off
	s_nop 0
	global_load_dwordx4 v[138:141], v[180:181], off offset:384
	s_nop 0
	global_load_dwordx4 v[158:161], v[158:159], off offset:384
.LBB0_1853:
	s_setprio 2
	ds_read_b128 v[194:197], v164 offset:55296
	ds_read_b128 v[224:227], v189 offset:18432
	ds_read_b128 v[228:231], v189 offset:23040
	ds_read_b128 v[232:235], v189 offset:27648
	ds_read_b128 v[236:239], v189 offset:32256
	s_andn2_b64 vcc, exec, s[8:9]
	ds_read_b128 v[240:243], v164 offset:55328
	ds_read_b128 v[190:193], v189 offset:18464
	s_waitcnt lgkmcnt(5)
	v_mfma_f32_32x32x16_bf16 v[0:15], v[224:227], v[194:197], v[0:15]
	ds_read_b128 v[198:201], v189 offset:23072
	s_waitcnt lgkmcnt(5)
	v_mfma_f32_32x32x16_bf16 v[16:31], v[228:231], v[194:197], v[16:31]
	ds_read_b128 v[224:227], v189 offset:27680
	s_waitcnt lgkmcnt(5)
	v_mfma_f32_32x32x16_bf16 v[34:49], v[232:235], v[194:197], v[34:49]
	ds_read_b128 v[228:231], v189 offset:32288
	s_waitcnt lgkmcnt(5)
	v_mfma_f32_32x32x16_bf16 v[50:65], v[236:239], v[194:197], v[50:65]
	ds_read_b128 v[194:197], v164 offset:55360
	ds_read_b128 v[232:235], v189 offset:18496
	s_waitcnt lgkmcnt(5)
	v_mfma_f32_32x32x16_bf16 v[0:15], v[190:193], v[240:243], v[0:15]
	ds_read_b128 v[236:239], v189 offset:23104
	s_waitcnt lgkmcnt(5)
	v_mfma_f32_32x32x16_bf16 v[16:31], v[198:201], v[240:243], v[16:31]
	ds_read_b128 v[190:193], v189 offset:27712
	s_waitcnt lgkmcnt(5)
	v_mfma_f32_32x32x16_bf16 v[34:49], v[224:227], v[240:243], v[34:49]
	ds_read_b128 v[198:201], v189 offset:32320
	s_waitcnt lgkmcnt(5)
	v_mfma_f32_32x32x16_bf16 v[50:65], v[228:231], v[240:243], v[50:65]
	ds_read_b128 v[240:243], v164 offset:55392
	ds_read_b128 v[224:227], v189 offset:18528
	s_waitcnt lgkmcnt(5)
	v_mfma_f32_32x32x16_bf16 v[0:15], v[232:235], v[194:197], v[0:15]
	ds_read_b128 v[228:231], v189 offset:23136
	s_waitcnt lgkmcnt(5)
	v_mfma_f32_32x32x16_bf16 v[16:31], v[236:239], v[194:197], v[16:31]
	ds_read_b128 v[232:235], v189 offset:27744
	s_waitcnt lgkmcnt(5)
	v_mfma_f32_32x32x16_bf16 v[34:49], v[190:193], v[194:197], v[34:49]
	ds_read_b128 v[236:239], v189 offset:32352
	s_waitcnt lgkmcnt(5)
	v_mfma_f32_32x32x16_bf16 v[50:65], v[198:201], v[194:197], v[50:65]
	s_waitcnt lgkmcnt(3)
	v_mfma_f32_32x32x16_bf16 v[0:15], v[224:227], v[240:243], v[0:15]
	s_waitcnt lgkmcnt(2)
	v_mfma_f32_32x32x16_bf16 v[16:31], v[228:231], v[240:243], v[16:31]
	s_waitcnt lgkmcnt(1)
	v_mfma_f32_32x32x16_bf16 v[34:49], v[232:235], v[240:243], v[34:49]
	s_waitcnt lgkmcnt(0)
	v_mfma_f32_32x32x16_bf16 v[50:65], v[236:239], v[240:243], v[50:65]
	s_setprio 0
	s_cbranch_vccnz .LBB0_1848
	s_waitcnt vmcnt(8)
	ds_write_b128 v166, v[66:69]
	ds_write_b128 v166, v[78:81] offset:36864
	ds_write_b128 v166, v[70:73] offset:4608
	ds_write_b128 v166, v[74:77] offset:41472
	ds_write_b128 v166, v[86:89] offset:9216
	ds_write_b128 v166, v[82:85] offset:46080
	ds_write_b128 v166, v[94:97] offset:13824
	ds_write_b128 v166, v[90:93] offset:50688
	s_branch .LBB0_1848
